# attention MODE0 steady loop: V-tile LDS-DMA issued at the start of the step (right after the barrier) for half a step more latency cover
# baseline (speedup 1.0000x reference)
.LBB0_798:
	v_add_u32_e32 v197, s10, v219
	ds_read_b64_tr_b16 v[184:185], v197 offset:24576
	ds_read_b64_tr_b16 v[186:187], v197 offset:25088
	s_add_i32 s10, s24, s47
	s_mov_b32 m0, s10
	s_nop 0
	global_load_lds_dwordx4 v203, s[98:99]
	v_mfma_f32_32x32x16_bf16 v[100:115], v[180:183], v[116:119], v[36:51]
	v_add_f32_e32 v84, v68, v69
	v_add_f32_e32 v84, v70, v84
	v_add_f32_e32 v84, v71, v84
	v_cvt_pk_bf16_f32 v148, v68, v69
	v_add_f32_e32 v84, v72, v84
	v_cvt_pk_bf16_f32 v149, v70, v71
	v_add_f32_e32 v84, v73, v84
	ds_read_b64_tr_b16 v[180:181], v197 offset:28672
	ds_read_b64_tr_b16 v[182:183], v197 offset:29184
	v_add_f32_e32 v68, v74, v84
	v_mfma_f32_32x32x16_bf16 v[84:99], v[176:179], v[116:119], v[36:51]
	v_add_f32_e32 v68, v75, v68
	v_add_f32_e32 v68, v76, v68
	v_add_f32_e32 v136, v77, v68
	v_cvt_pk_bf16_f32 v150, v72, v73
	v_cvt_pk_bf16_f32 v151, v74, v75
	ds_read_b64_tr_b16 v[68:69], v197 offset:25600
	ds_read_b64_tr_b16 v[70:71], v197 offset:26112
	v_mfma_f32_32x32x16_bf16 v[100:115], v[172:175], v[120:123], v[100:115]
	v_add_f32_e32 v72, v78, v136
	v_add_f32_e32 v72, v79, v72
	v_add_f32_e32 v72, v80, v72
	v_add_f32_e32 v136, v81, v72
	v_cvt_pk_bf16_f32 v144, v76, v77
	v_cvt_pk_bf16_f32 v145, v78, v79
	ds_read_b64_tr_b16 v[72:73], v197 offset:29696
	ds_read_b64_tr_b16 v[74:75], v197 offset:30208
	v_mfma_f32_32x32x16_bf16 v[84:99], v[168:171], v[120:123], v[84:99]
	v_add_f32_e32 v76, v82, v136
	v_add_f32_e32 v76, v83, v76
	v_add_f32_e32 v76, v52, v76
	v_add_f32_e32 v136, v53, v76
	v_cvt_pk_bf16_f32 v146, v80, v81
	v_cvt_pk_bf16_f32 v147, v82, v83
	ds_read_b64_tr_b16 v[76:77], v197 offset:26624
	ds_read_b64_tr_b16 v[78:79], v197 offset:27136
	v_mfma_f32_32x32x16_bf16 v[100:115], v[164:167], v[124:127], v[100:115]
	v_add_f32_e32 v80, v54, v136
	v_add_f32_e32 v80, v55, v80
	v_cvt_pk_bf16_f32 v140, v52, v53
	v_add_f32_e32 v80, v56, v80
	v_cvt_pk_bf16_f32 v141, v54, v55
	v_add_f32_e32 v80, v57, v80
	ds_read_b64_tr_b16 v[52:53], v197 offset:30720
	ds_read_b64_tr_b16 v[54:55], v197 offset:31232
	v_mfma_f32_32x32x16_bf16 v[84:99], v[160:163], v[124:127], v[84:99]
	v_add_f32_e32 v80, v58, v80
	v_add_f32_e32 v80, v59, v80
	v_cvt_pk_bf16_f32 v142, v56, v57
	v_add_f32_e32 v80, v60, v80
	v_cvt_pk_bf16_f32 v143, v58, v59
	v_add_f32_e32 v80, v61, v80
	ds_read_b64_tr_b16 v[56:57], v197 offset:27648
	ds_read_b64_tr_b16 v[58:59], v197 offset:28160
	v_mfma_f32_32x32x16_bf16 v[100:115], v[156:159], v[128:131], v[100:115]
	v_add_f32_e32 v80, v62, v80
	v_add_f32_e32 v80, v63, v80
	v_cvt_pk_bf16_f32 v136, v60, v61
	v_add_f32_e32 v80, v64, v80
	v_cvt_pk_bf16_f32 v137, v62, v63
	v_add_f32_e32 v80, v65, v80
	ds_read_b64_tr_b16 v[60:61], v197 offset:31744
	ds_read_b64_tr_b16 v[62:63], v197 offset:32256
	v_mfma_f32_32x32x16_bf16 v[84:99], v[152:155], v[128:131], v[84:99]
	v_add_f32_e32 v80, v66, v80
	v_cvt_pk_bf16_f32 v138, v64, v65
	v_add_f32_e32 v80, v67, v80
	v_cvt_pk_bf16_f32 v139, v66, v67
	s_add_i32 s10, s25, s46
	s_mov_b32 m0, s10
	s_nop 0
	global_load_lds_dwordx4 v202, s[98:99]
	v_add_f32_e32 v204, v220, v80

.LBB0_801:
	v_add_u32_e32 v197, s25, v219
	ds_read_b64_tr_b16 v[152:153], v197 offset:24576
	ds_read_b64_tr_b16 v[154:155], v197 offset:25088
	s_add_i32 s10, s54, s47
	s_mov_b32 m0, s10
	s_nop 0
	global_load_lds_dwordx4 v199, s[98:99]
	v_mfma_f32_32x32x16_bf16 v[68:83], v[64:67], v[116:119], v[36:51]
	v_add_f32_e32 v52, v100, v101
	v_add_f32_e32 v52, v102, v52
	v_add_f32_e32 v52, v103, v52
	v_cvt_pk_bf16_f32 v148, v100, v101
	v_add_f32_e32 v52, v104, v52
	v_cvt_pk_bf16_f32 v149, v102, v103
	v_add_f32_e32 v52, v105, v52
	ds_read_b64_tr_b16 v[156:157], v197 offset:28672
	ds_read_b64_tr_b16 v[158:159], v197 offset:29184
	v_add_f32_e32 v52, v106, v52
	v_add_f32_e32 v52, v107, v52
	v_add_f32_e32 v52, v108, v52
	v_add_f32_e32 v136, v109, v52
	v_mfma_f32_32x32x16_bf16 v[52:67], v[180:183], v[116:119], v[36:51]
	v_cvt_pk_bf16_f32 v150, v104, v105
	v_cvt_pk_bf16_f32 v151, v106, v107
	ds_read_b64_tr_b16 v[100:101], v197 offset:25600
	ds_read_b64_tr_b16 v[102:103], v197 offset:26112
	v_mfma_f32_32x32x16_bf16 v[68:83], v[184:187], v[120:123], v[68:83]
	v_add_f32_e32 v104, v110, v136
	v_add_f32_e32 v104, v111, v104
	v_add_f32_e32 v104, v112, v104
	v_add_f32_e32 v136, v113, v104
	v_cvt_pk_bf16_f32 v144, v108, v109
	v_cvt_pk_bf16_f32 v145, v110, v111
	ds_read_b64_tr_b16 v[104:105], v197 offset:29696
	ds_read_b64_tr_b16 v[106:107], v197 offset:30208
	v_mfma_f32_32x32x16_bf16 v[52:67], v[176:179], v[120:123], v[52:67]
	v_add_f32_e32 v108, v114, v136
	v_add_f32_e32 v108, v115, v108
	v_add_f32_e32 v108, v84, v108
	v_add_f32_e32 v136, v85, v108
	v_cvt_pk_bf16_f32 v146, v112, v113
	v_cvt_pk_bf16_f32 v147, v114, v115
	ds_read_b64_tr_b16 v[108:109], v197 offset:26624
	ds_read_b64_tr_b16 v[110:111], v197 offset:27136
	v_mfma_f32_32x32x16_bf16 v[68:83], v[172:175], v[124:127], v[68:83]
	v_add_f32_e32 v112, v86, v136
	v_add_f32_e32 v112, v87, v112
	v_cvt_pk_bf16_f32 v140, v84, v85
	v_add_f32_e32 v112, v88, v112
	v_cvt_pk_bf16_f32 v141, v86, v87
	v_add_f32_e32 v112, v89, v112
	ds_read_b64_tr_b16 v[84:85], v197 offset:30720
	ds_read_b64_tr_b16 v[86:87], v197 offset:31232
	v_mfma_f32_32x32x16_bf16 v[52:67], v[168:171], v[124:127], v[52:67]
	v_add_f32_e32 v112, v90, v112
	v_add_f32_e32 v112, v91, v112
	v_cvt_pk_bf16_f32 v142, v88, v89
	v_add_f32_e32 v112, v92, v112
	v_cvt_pk_bf16_f32 v143, v90, v91
	v_add_f32_e32 v112, v93, v112
	ds_read_b64_tr_b16 v[88:89], v197 offset:27648
	ds_read_b64_tr_b16 v[90:91], v197 offset:28160
	v_mfma_f32_32x32x16_bf16 v[68:83], v[164:167], v[128:131], v[68:83]
	v_add_f32_e32 v112, v94, v112
	v_add_f32_e32 v112, v95, v112
	v_cvt_pk_bf16_f32 v136, v92, v93
	v_add_f32_e32 v112, v96, v112
	v_cvt_pk_bf16_f32 v137, v94, v95
	v_add_f32_e32 v112, v97, v112
	ds_read_b64_tr_b16 v[92:93], v197 offset:31744
	ds_read_b64_tr_b16 v[94:95], v197 offset:32256
	v_mfma_f32_32x32x16_bf16 v[52:67], v[160:163], v[128:131], v[52:67]
	v_add_f32_e32 v112, v98, v112
	v_cvt_pk_bf16_f32 v138, v96, v97
	v_add_f32_e32 v112, v99, v112
	v_cvt_pk_bf16_f32 v139, v98, v99
	v_add_f32_e32 v220, v204, v112
	s_add_i32 s10, s24, s46
	s_mov_b32 m0, s10
	s_nop 0
	global_load_lds_dwordx4 v198, s[98:99]
